# NSA selected/window tile bodies: K fragment reads hoisted together with the V reads; prep_weights round-robin starts at wave 256 so the pe-bias workgroups get the lighter share
# baseline (speedup 1.0000x reference)
; __device__ __forceinline__ int otid() { int t = threadIdx.x; asm volatile("" : "+v"(t)); return t; }
; __device__ __forceinline__ void prep_weights(lptr L, const Params& P, int l) {
;     const int tid = otid(), lane = tid & 63, wave = tid >> 6;
;     const int gw = blockIdx.x * 8 + wave, NGW = gridDim.x * 8;
;     const lptr scr = L + wave * 8704;
;     unsigned char* ws = P.ws;
; #pragma unroll 1
;     for (int mi = 0; mi < 14; ++mi) {
;     ...
;         for (int it = gw; it < nitems; it += NGW) {
.LBB0_880:
	s_andn2_b64 vcc, exec, s[2:3]
	s_cbranch_vccnz .LBB0_941
	s_cmp_lg_u32 s76, 0
	s_cbranch_scc1 .LBB0_941
	v_mov_b32_e32 v13, v193
	v_readlane_b32 s0, v252, 40
	v_bfe_u32 v19, v13, 3, 3
	v_lshlrev_b32_e32 v0, 2, v13
	v_and_b32_e32 v0, 28, v0
	v_mul_u32_u24_e32 v2, 33, v19
	v_add_lshl_u32 v20, v2, v0, 2
	v_lshlrev_b32_e32 v2, 3, v13
	v_and_b32_e32 v2, 56, v2
	v_ashrrev_i32_e32 v3, 6, v13
	v_mul_u32_u24_e32 v6, 33, v2
	v_add_u32_e32 v15, s0, v3
	s_movk_i32 s0, 0x2200
	v_or_b32_e32 v21, 8, v19
	v_or_b32_e32 v22, 16, v19
	v_or_b32_e32 v23, 24, v19
	v_or_b32_e32 v8, v6, v19
	v_mul_lo_u32 v18, v3, s0
	v_add_u32_e32 v4, 0x420, v20
	v_add_u32_e32 v5, 0x840, v20
	v_add_u32_e32 v7, 0xc60, v20
	v_lshlrev_b32_e32 v8, 2, v8
	v_add_lshl_u32 v9, v6, v21, 2
	v_add_lshl_u32 v10, v6, v22, 2
	v_add_lshl_u32 v11, v6, v23, 2
	v_readlane_b32 s0, v255, 7
	s_mov_b32 s5, 0
	s_movk_i32 s99, 0x100
	v_lshlrev_b32_e32 v0, 2, v0
	v_lshl_add_u32 v24, v3, 5, s0
	v_lshlrev_b32_e32 v6, 1, v2
	v_add_u32_e32 v25, v18, v4
	v_add_u32_e32 v26, v18, v5
	v_add_u32_e32 v27, v18, v7
	v_add_u32_e32 v28, v18, v8
	v_add_u32_e32 v29, v18, v9
	v_add_u32_e32 v30, v18, v10
	v_add_u32_e32 v31, v18, v11
	s_branch .LBB0_884
